# hyena loops: prefetch only the U fragments the next lag uses
# speedup vs baseline: 1.0769x; 1.0024x over previous
; #define MFMA(a, b, c) __builtin_amdgcn_mfma_f32_32x32x16_bf16((a), (b), (c), 0, 0, 0)
; DI void hy_conv(const bf16_t* ub, const bf16_t* filt, f32x16 (&acc)[2], int nbase, int li, int lh) {
;     const int klo = 32 * nbase - 127, khi = 32 * (nbase + 1) + 31;
;     const int m0 = 4096 + li - 8 * lh - 7;
;     const unsigned sh = (unsigned)(m0 & 1) * 16u;
;     const unsigned* fd0 = (const unsigned*)filt + (m0 >> 1);
;     unsigned raw[10];
;     hy_rawload(fd0 + 16 * klo, raw);
; #pragma unroll 4
;     for (int k = klo; k <= khi; ++k) {
;         u32x4 ua, ub4;
;         ua.x = __builtin_amdgcn_alignbit(raw[1], raw[0], sh); ua.y = __builtin_amdgcn_alignbit(raw[2], raw[1], sh); ua.z = __builtin_amdgcn_alignbit(raw[3], raw[2], sh); ua.w = __builtin_amdgcn_alignbit(raw[4], raw[3], sh);
;         ub4.x = __builtin_amdgcn_alignbit(raw[6], raw[5], sh); ub4.y = __builtin_amdgcn_alignbit(raw[7], raw[6], sh); ub4.z = __builtin_amdgcn_alignbit(raw[8], raw[7], sh); ub4.w = __builtin_amdgcn_alignbit(raw[9], raw[8], sh);
;         const bf16x8 a0 = __builtin_bit_cast(bf16x8, ua), a1 = __builtin_bit_cast(bf16x8, ub4);
;         if (k < khi) hy_rawload(fd0 + 16 * (k + 1), raw);
;         bf16x8 b0[2], b1[2]; bool use[2];
; #pragma unroll
;         for (int n = 0; n < 2; ++n) {
;             const int nn = nbase + n; use[n] = (k >= 32 * nn - 127) && (k <= 32 * nn + 31);
;             const int c = 32 * nn + li - k;
;             const bf16_t* up = ub + c * 40 + 8 * lh;
;             b0[n] = ld8(up); b1[n] = ld8(up + 16);
;         }
; #pragma unroll
;         for (int n = 0; n < 2; ++n) if (use[n]) { acc[n] = MFMA(a0, b0[n], acc[n]); acc[n] = MFMA(a1, b1[n], acc[n]); }
;     }
; DI void hyena_lat_item(const Params& p, int layer, int it, unsigned char* smem) {
;     ...
;       for (int j = 0; j < 4; ++j) *(u32x4*)(Fl + (tid + 256 * j) * 8) = sf[j];
;       if (tid < 8) ((unsigned*)(Fl + 8192))[tid] = 0u; }
;     __syncthreads();
;     const float inv0 = 1.f / (red[0] + red[1] + red[2] + red[3] + EPS), inv1 = 1.f / (red[4] + red[5] + red[6] + red[7] + EPS);
;     const float d0 = p.in[I_DSH][layer * 512 + ch], d1 = p.in[I_DSH][layer * 512 + 256 + ch];
;     bf16_t* ub = U + bl * UB;
;     f32x16 acc[2];
;     acc[0] = zero16(); acc[1] = zero16();
;     hy_conv(ub, Fl, acc, nbase, li, lh);
.LBB0_432:
	s_or_b64 exec, exec, s[12:13]
	v_add_u32_e32 v106, 0, v1
	v_cmp_gt_i32_e32 vcc, 8, v70
	s_waitcnt vmcnt(3)
	ds_write_b128 v106, v[4:7] offset:30720
	s_waitcnt vmcnt(2)
	ds_write_b128 v106, v[8:11] offset:34816
	s_waitcnt vmcnt(1)
	ds_write_b128 v106, v[12:15] offset:38912
	s_waitcnt vmcnt(0)
	ds_write_b128 v106, v[16:19] offset:43008
	s_and_saveexec_b64 s[12:13], vcc
	v_lshl_add_u32 v1, v70, 2, 0
	ds_write_b32 v1, v3 offset:47104
	s_or_b64 exec, exec, s[12:13]
	v_readlane_b32 s9, v255, 36
	s_or_b32 s8, s8, s9
	s_ashr_i32 s9, s8, 31
	v_readlane_b32 s40, v253, 0
	s_lshl_b64 s[8:9], s[8:9], 2
	v_readlane_b32 s54, v253, 14
	v_readlane_b32 s55, v253, 15
	s_add_u32 s8, s54, s8
	s_addc_u32 s9, s55, s9
	s_waitcnt lgkmcnt(0)
	s_barrier
	global_load_dword v71, v3, s[8:9]
	global_load_dword v61, v3, s[8:9] offset:1024
	v_lshrrev_b32_e32 v112, 5, v0
	v_ashrrev_i32_e32 v75, 7, v70
	v_and_b32_e32 v97, 31, v70
	v_mul_lo_u32 v0, v75, s38
	v_lshlrev_b32_e32 v74, 3, v112
	v_add_u32_e32 v113, 0, v0
	v_sub_u32_e32 v0, v97, v74
	v_add_u32_e32 v0, 0xff9, v0
	v_and_b32_e32 v98, 64, v70
	v_lshlrev_b32_e32 v96, 4, v0
	v_lshlrev_b32_e32 v0, 1, v0
	v_and_b32_e32 v0, 0x3ffc, v0
	v_or_b32_e32 v101, 0xffffff81, v98
	v_add_u32_e32 v100, 0, v0
	v_lshlrev_b32_e32 v0, 6, v101
	v_add_u32_e32 v0, v100, v0
	v_add_u32_e32 v107, 0x7800, v0
	v_add_u32_e32 v111, 0x7600, v0
	ds_read_b128 v[40:43], v3 offset:47136
	ds_read_b128 v[36:39], v3 offset:47152
	v_add_u32_e32 v108, 0x7808, v0
	ds_read2_b32 v[72:73], v111 offset0:124 offset1:132
	v_add_u32_e32 v109, 0x77e0, v0
	v_add_u32_e32 v110, 0x77e8, v0
	ds_read2_b32 v[80:81], v107 offset1:1
	ds_read2_b32 v[82:83], v108 offset1:1
	ds_read2_b32 v[76:77], v109 offset1:1
	ds_read2_b32 v[78:79], v110 offset1:1
	v_mov_b32_e32 v14, v3
	v_mov_b32_e32 v15, v3
	v_mov_b32_e32 v0, v3
	v_mov_b32_e32 v1, v3
	v_mov_b32_e32 v2, v3
	v_mov_b32_e32 v4, v3
	v_mov_b32_e32 v5, v3
	v_mov_b32_e32 v6, v3
	v_mov_b32_e32 v7, v3
	v_mov_b32_e32 v8, v3
	v_mov_b32_e32 v9, v3
	v_mov_b32_e32 v10, v3
	v_mov_b32_e32 v11, v3
	v_mov_b32_e32 v12, v3
	v_mov_b32_e32 v13, v3
	v_mov_b64_e32 v[34:35], v[14:15]
	v_mov_b64_e32 v[32:33], v[12:13]
	v_mov_b64_e32 v[30:31], v[10:11]
	v_mov_b64_e32 v[28:29], v[8:9]
	v_mov_b64_e32 v[26:27], v[6:7]
	v_mov_b64_e32 v[24:25], v[4:5]
	v_mov_b64_e32 v[22:23], v[2:3]
	v_mov_b64_e32 v[20:21], v[0:1]
	v_mov_b64_e32 v[18:19], v[14:15]
	v_or_b32_e32 v99, 63, v98
	v_lshl_add_u32 v60, v112, 4, v113
	v_or_b32_e32 v102, 31, v98
	v_or_b32_e32 v103, 32, v98
	v_or_b32_e32 v104, 0xffffffa1, v98
	v_or_b32_e32 v105, 62, v98
	s_mov_b64 s[12:13], 0
	v_mov_b64_e32 v[16:17], v[12:13]
	v_mov_b64_e32 v[14:15], v[10:11]
	v_mov_b64_e32 v[12:13], v[8:9]
	v_mov_b64_e32 v[10:11], v[6:7]
	v_mov_b64_e32 v[8:9], v[4:5]
	v_mov_b64_e32 v[6:7], v[2:3]
	v_mov_b64_e32 v[4:5], v[0:1]
	v_mov_b32_e32 v2, v101
	v_readlane_b32 s41, v253, 1
	v_readlane_b32 s42, v253, 2
	v_readlane_b32 s43, v253, 3
	v_readlane_b32 s44, v253, 4
	v_readlane_b32 s45, v253, 5
	v_readlane_b32 s46, v253, 6
	v_readlane_b32 s47, v253, 7
	v_readlane_b32 s48, v253, 8
	v_readlane_b32 s49, v253, 9
	v_readlane_b32 s50, v253, 10
	v_readlane_b32 s51, v253, 11
	v_readlane_b32 s52, v253, 12
	v_readlane_b32 s53, v253, 13
	v_add_u32_e32 v164, 0xffffffe0, v107
	v_add_u32_e32 v165, v98, v97
	v_sub_u32_e32 v165, v165, v101
	v_add_u32_e32 v165, -2, v165
	v_mad_u32_u24 v165, v165, s88, v60
	ds_read2_b32 v[194:195], v164 offset0:0 offset1:1
	ds_read2_b32 v[196:197], v164 offset0:2 offset1:3
	ds_read2_b32 v[198:199], v164 offset0:4 offset1:8
	ds_read2_b32 v[200:201], v164 offset0:9 offset1:10
	ds_read2_b32 v[202:203], v164 offset0:11 offset1:12
	ds_read_b128 v[214:217], v165 offset:2720
	ds_read_b128 v[218:221], v165 offset:2752
	s_mov_b32 s8, 15
.Lhy1_a:
	ds_read2_b32 v[204:205], v164 offset0:16 offset1:17
	ds_read2_b32 v[206:207], v164 offset0:18 offset1:19
	ds_read2_b32 v[208:209], v164 offset0:20 offset1:24
	ds_read2_b32 v[210:211], v164 offset0:25 offset1:26
	ds_read2_b32 v[212:213], v164 offset0:27 offset1:28
	ds_read_b128 v[174:177], v165 offset:2640
	ds_read_b128 v[178:181], v165 offset:2672
	s_waitcnt lgkmcnt(7)
	v_alignbit_b32 v156, v200, v199, v96
	v_alignbit_b32 v157, v201, v200, v96
	v_alignbit_b32 v158, v202, v201, v96
	v_alignbit_b32 v159, v203, v202, v96
	v_alignbit_b32 v160, v195, v194, v96
	v_alignbit_b32 v161, v196, v195, v96
	v_alignbit_b32 v162, v197, v196, v96
	v_alignbit_b32 v163, v198, v197, v96
	s_nop 0
	v_mfma_f32_32x32x16_bf16 v[20:35], v[156:159], v[214:217], v[20:35]
	v_mfma_f32_32x32x16_bf16 v[20:35], v[160:163], v[218:221], v[20:35]
	ds_read2_b32 v[194:195], v164 offset0:32 offset1:33
	ds_read2_b32 v[196:197], v164 offset0:34 offset1:35
	ds_read2_b32 v[198:199], v164 offset0:36 offset1:40
	ds_read2_b32 v[200:201], v164 offset0:41 offset1:42
	ds_read2_b32 v[202:203], v164 offset0:43 offset1:44
	ds_read_b128 v[214:217], v165 offset:2560
	ds_read_b128 v[218:221], v165 offset:2592
	s_waitcnt lgkmcnt(7)
	v_alignbit_b32 v156, v210, v209, v96
	v_alignbit_b32 v157, v211, v210, v96
	v_alignbit_b32 v158, v212, v211, v96
	v_alignbit_b32 v159, v213, v212, v96
	v_alignbit_b32 v160, v205, v204, v96
	v_alignbit_b32 v161, v206, v205, v96
	v_alignbit_b32 v162, v207, v206, v96
	v_alignbit_b32 v163, v208, v207, v96
	s_nop 0
	v_mfma_f32_32x32x16_bf16 v[20:35], v[156:159], v[174:177], v[20:35]
	v_mfma_f32_32x32x16_bf16 v[20:35], v[160:163], v[178:181], v[20:35]
	v_add_u32_e32 v164, 0x80, v164
	v_add_u32_e32 v165, 0xffffff60, v165
	s_sub_u32 s8, s8, 1
	s_cmp_lg_u32 s8, 0
	s_cbranch_scc1 .Lhy1_a
; #define MFMA(a, b, c) __builtin_amdgcn_mfma_f32_32x32x16_bf16((a), (b), (c), 0, 0, 0)
; DI void hy_conv(const bf16_t* ub, const bf16_t* filt, f32x16 (&acc)[2], int nbase, int li, int lh) {
;     const int klo = 32 * nbase - 127, khi = 32 * (nbase + 1) + 31;
;     const int m0 = 4096 + li - 8 * lh - 7;
;     const unsigned sh = (unsigned)(m0 & 1) * 16u;
;     const unsigned* fd0 = (const unsigned*)filt + (m0 >> 1);
;     unsigned raw[10];
;     hy_rawload(fd0 + 16 * klo, raw);
; #pragma unroll 4
;     for (int k = klo; k <= khi; ++k) {
;         u32x4 ua, ub4;
;         ua.x = __builtin_amdgcn_alignbit(raw[1], raw[0], sh); ua.y = __builtin_amdgcn_alignbit(raw[2], raw[1], sh); ua.z = __builtin_amdgcn_alignbit(raw[3], raw[2], sh); ua.w = __builtin_amdgcn_alignbit(raw[4], raw[3], sh);
;         ub4.x = __builtin_amdgcn_alignbit(raw[6], raw[5], sh); ub4.y = __builtin_amdgcn_alignbit(raw[7], raw[6], sh); ub4.z = __builtin_amdgcn_alignbit(raw[8], raw[7], sh); ub4.w = __builtin_amdgcn_alignbit(raw[9], raw[8], sh);
;         const bf16x8 a0 = __builtin_bit_cast(bf16x8, ua), a1 = __builtin_bit_cast(bf16x8, ub4);
;         if (k < khi) hy_rawload(fd0 + 16 * (k + 1), raw);
;         bf16x8 b0[2], b1[2]; bool use[2];
; #pragma unroll
;         for (int n = 0; n < 2; ++n) {
;             const int nn = nbase + n; use[n] = (k >= 32 * nn - 127) && (k <= 32 * nn + 31);
;             const int c = 32 * nn + li - k;
;             const bf16_t* up = ub + c * 40 + 8 * lh;
;             b0[n] = ld8(up); b1[n] = ld8(up + 16);
;         }
; #pragma unroll
;         for (int n = 0; n < 2; ++n) if (use[n]) { acc[n] = MFMA(a0, b0[n], acc[n]); acc[n] = MFMA(a1, b1[n], acc[n]); }
;     }
	ds_read2_b32 v[204:205], v164 offset0:16 offset1:17
	ds_read2_b32 v[206:207], v164 offset0:18 offset1:19
	ds_read2_b32 v[208:209], v164 offset0:20 offset1:24
	ds_read2_b32 v[210:211], v164 offset0:25 offset1:26
	ds_read2_b32 v[212:213], v164 offset0:27 offset1:28
	ds_read_b128 v[174:177], v165 offset:2640
	ds_read_b128 v[178:181], v165 offset:2672
	s_waitcnt lgkmcnt(7)
	v_alignbit_b32 v156, v200, v199, v96
	v_alignbit_b32 v157, v201, v200, v96
	v_alignbit_b32 v158, v202, v201, v96
	v_alignbit_b32 v159, v203, v202, v96
	v_alignbit_b32 v160, v195, v194, v96
	v_alignbit_b32 v161, v196, v195, v96
	v_alignbit_b32 v162, v197, v196, v96
	v_alignbit_b32 v163, v198, v197, v96
	s_nop 0
	v_mfma_f32_32x32x16_bf16 v[20:35], v[156:159], v[214:217], v[20:35]
	v_mfma_f32_32x32x16_bf16 v[20:35], v[160:163], v[218:221], v[20:35]
	ds_read2_b32 v[194:195], v164 offset0:32 offset1:33
	ds_read2_b32 v[196:197], v164 offset0:34 offset1:35
	ds_read2_b32 v[198:199], v164 offset0:36 offset1:40
	ds_read2_b32 v[200:201], v164 offset0:41 offset1:42
	ds_read2_b32 v[202:203], v164 offset0:43 offset1:44
	ds_read_b128 v[214:217], v165 offset:2560
	ds_read_b128 v[218:221], v165 offset:2592
	ds_read_b128 v[222:225], v165 offset:5120
	ds_read_b128 v[226:229], v165 offset:5152
	s_waitcnt lgkmcnt(9)
	v_alignbit_b32 v156, v210, v209, v96
	v_alignbit_b32 v157, v211, v210, v96
	v_alignbit_b32 v158, v212, v211, v96
	v_alignbit_b32 v159, v213, v212, v96
	v_alignbit_b32 v160, v205, v204, v96
	v_alignbit_b32 v161, v206, v205, v96
	v_alignbit_b32 v162, v207, v206, v96
	v_alignbit_b32 v163, v208, v207, v96
	s_nop 0
	v_mfma_f32_32x32x16_bf16 v[20:35], v[156:159], v[174:177], v[20:35]
	v_mfma_f32_32x32x16_bf16 v[20:35], v[160:163], v[178:181], v[20:35]
	v_add_u32_e32 v164, 0x80, v164
	v_add_u32_e32 v165, 0xffffff60, v165
	s_mov_b32 s8, 63
.Lhy1_b:
	ds_read2_b32 v[204:205], v164 offset0:16 offset1:17
	ds_read2_b32 v[206:207], v164 offset0:18 offset1:19
	ds_read2_b32 v[208:209], v164 offset0:20 offset1:24
	ds_read2_b32 v[210:211], v164 offset0:25 offset1:26
	ds_read2_b32 v[212:213], v164 offset0:27 offset1:28
	ds_read_b128 v[174:177], v165 offset:2640
	ds_read_b128 v[178:181], v165 offset:2672
	ds_read_b128 v[230:233], v165 offset:5200
	ds_read_b128 v[152:155], v165 offset:5232
	s_waitcnt lgkmcnt(9)
	v_alignbit_b32 v156, v200, v199, v96
	v_alignbit_b32 v157, v201, v200, v96
	v_alignbit_b32 v158, v202, v201, v96
	v_alignbit_b32 v159, v203, v202, v96
	v_alignbit_b32 v160, v195, v194, v96
	v_alignbit_b32 v161, v196, v195, v96
	v_alignbit_b32 v162, v197, v196, v96
	v_alignbit_b32 v163, v198, v197, v96
	v_mfma_f32_32x32x16_bf16 v[20:35], v[156:159], v[214:217], v[20:35]
	v_mfma_f32_32x32x16_bf16 v[4:19], v[156:159], v[222:225], v[4:19]
	v_mfma_f32_32x32x16_bf16 v[20:35], v[160:163], v[218:221], v[20:35]
	v_mfma_f32_32x32x16_bf16 v[4:19], v[160:163], v[226:229], v[4:19]
	ds_read2_b32 v[194:195], v164 offset0:32 offset1:33
	ds_read2_b32 v[196:197], v164 offset0:34 offset1:35
	ds_read2_b32 v[198:199], v164 offset0:36 offset1:40
	ds_read2_b32 v[200:201], v164 offset0:41 offset1:42
	ds_read2_b32 v[202:203], v164 offset0:43 offset1:44
	ds_read_b128 v[214:217], v165 offset:2560
	ds_read_b128 v[218:221], v165 offset:2592
	ds_read_b128 v[222:225], v165 offset:5120
	ds_read_b128 v[226:229], v165 offset:5152
	s_waitcnt lgkmcnt(9)
	v_alignbit_b32 v156, v210, v209, v96
	v_alignbit_b32 v157, v211, v210, v96
	v_alignbit_b32 v158, v212, v211, v96
	v_alignbit_b32 v159, v213, v212, v96
	v_alignbit_b32 v160, v205, v204, v96
	v_alignbit_b32 v161, v206, v205, v96
	v_alignbit_b32 v162, v207, v206, v96
	v_alignbit_b32 v163, v208, v207, v96
	v_mfma_f32_32x32x16_bf16 v[20:35], v[156:159], v[174:177], v[20:35]
	v_mfma_f32_32x32x16_bf16 v[4:19], v[156:159], v[230:233], v[4:19]
	v_mfma_f32_32x32x16_bf16 v[20:35], v[160:163], v[178:181], v[20:35]
	v_mfma_f32_32x32x16_bf16 v[4:19], v[160:163], v[152:155], v[4:19]
	v_add_u32_e32 v164, 0x80, v164
	v_add_u32_e32 v165, 0xffffff60, v165
	s_sub_u32 s8, s8, 1
	s_cmp_lg_u32 s8, 0
	s_cbranch_scc1 .Lhy1_b
	ds_read2_b32 v[204:205], v164 offset0:16 offset1:17
	ds_read2_b32 v[206:207], v164 offset0:18 offset1:19
	ds_read2_b32 v[208:209], v164 offset0:20 offset1:24
	ds_read2_b32 v[210:211], v164 offset0:25 offset1:26
	ds_read2_b32 v[212:213], v164 offset0:27 offset1:28
	ds_read_b128 v[230:233], v165 offset:5200
	ds_read_b128 v[152:155], v165 offset:5232
	s_waitcnt lgkmcnt(7)
	v_alignbit_b32 v156, v200, v199, v96
	v_alignbit_b32 v157, v201, v200, v96
	v_alignbit_b32 v158, v202, v201, v96
	v_alignbit_b32 v159, v203, v202, v96
	v_alignbit_b32 v160, v195, v194, v96
	v_alignbit_b32 v161, v196, v195, v96
	v_alignbit_b32 v162, v197, v196, v96
	v_alignbit_b32 v163, v198, v197, v96
	v_mfma_f32_32x32x16_bf16 v[20:35], v[156:159], v[214:217], v[20:35]
	v_mfma_f32_32x32x16_bf16 v[4:19], v[156:159], v[222:225], v[4:19]
	v_mfma_f32_32x32x16_bf16 v[20:35], v[160:163], v[218:221], v[20:35]
	v_mfma_f32_32x32x16_bf16 v[4:19], v[160:163], v[226:229], v[4:19]
	v_add_u32_e32 v164, 64, v164
	v_add_u32_e32 v165, 0xffffffb0, v165
	s_mov_b32 s8, 15
; #define MFMA(a, b, c) __builtin_amdgcn_mfma_f32_32x32x16_bf16((a), (b), (c), 0, 0, 0)
; DI void hy_conv(const bf16_t* ub, const bf16_t* filt, f32x16 (&acc)[2], int nbase, int li, int lh) {
;     ...
; #pragma unroll 4
;     for (int k = klo; k <= khi; ++k) {
;         u32x4 ua, ub4;
;         ua.x = __builtin_amdgcn_alignbit(raw[1], raw[0], sh); ua.y = __builtin_amdgcn_alignbit(raw[2], raw[1], sh); ua.z = __builtin_amdgcn_alignbit(raw[3], raw[2], sh); ua.w = __builtin_amdgcn_alignbit(raw[4], raw[3], sh);
;         ub4.x = __builtin_amdgcn_alignbit(raw[6], raw[5], sh); ub4.y = __builtin_amdgcn_alignbit(raw[7], raw[6], sh); ub4.z = __builtin_amdgcn_alignbit(raw[8], raw[7], sh); ub4.w = __builtin_amdgcn_alignbit(raw[9], raw[8], sh);
;         const bf16x8 a0 = __builtin_bit_cast(bf16x8, ua), a1 = __builtin_bit_cast(bf16x8, ub4);
;         if (k < khi) hy_rawload(fd0 + 16 * (k + 1), raw);
;         bf16x8 b0[2], b1[2]; bool use[2];
; #pragma unroll
;         for (int n = 0; n < 2; ++n) {
;             const int nn = nbase + n; use[n] = (k >= 32 * nn - 127) && (k <= 32 * nn + 31);
;             const int c = 32 * nn + li - k;
;             const bf16_t* up = ub + c * 40 + 8 * lh;
;             b0[n] = ld8(up); b1[n] = ld8(up + 16);
;         }
; #pragma unroll
;         for (int n = 0; n < 2; ++n) if (use[n]) { acc[n] = MFMA(a0, b0[n], acc[n]); acc[n] = MFMA(a1, b1[n], acc[n]); }
; DI void hyena_lat_item(const Params& p, int layer, int it, unsigned char* smem) {
;     ...
;     const float inv0 = 1.f / (red[0] + red[1] + red[2] + red[3] + EPS), inv1 = 1.f / (red[4] + red[5] + red[6] + red[7] + EPS);
;     const float d0 = p.in[I_DSH][layer * 512 + ch], d1 = p.in[I_DSH][layer * 512 + 256 + ch];
;     bf16_t* ub = U + bl * UB;
;     f32x16 acc[2];
;     acc[0] = zero16(); acc[1] = zero16();
;     hy_conv(ub, Fl, acc, nbase, li, lh);
;     __syncthreads();
;     { u32x4 sf[4];
; #pragma unroll
;       for (int j = 0; j < 4; ++j) sf[j] = *(const u32x4*)(FL + (size_t)(1 * 256 + ch) * 8192 + (tid + 256 * j) * 8);
; #pragma unroll
;       for (int n = 0; n < 2; ++n)
; #pragma unroll
;         for (int rg = 0; rg < 4; ++rg) {
;             const int a = 32 * (nbase + n) + li, ii = 8 * rg + 4 * lh; bf16_t* up = ub + a * 40 + 8 * rg + 4 * (1 - lh);
;             const u32x2 zz = *(const u32x2*)up; const u32x2 pp = *(const u32x2*)(P + (size_t)(256 + ch) * NT + bg * SEQ + 32 * a + ii);
.Lhy1_c:
	ds_read2_b32 v[194:195], v164 offset0:16 offset1:17
	ds_read2_b32 v[196:197], v164 offset0:18 offset1:19
	ds_read2_b32 v[198:199], v164 offset0:20 offset1:24
	ds_read2_b32 v[200:201], v164 offset0:25 offset1:26
	ds_read2_b32 v[202:203], v164 offset0:27 offset1:28
	ds_read_b128 v[222:225], v165 offset:5200
	ds_read_b128 v[226:229], v165 offset:5232
	s_waitcnt lgkmcnt(7)
	v_alignbit_b32 v156, v210, v209, v96
	v_alignbit_b32 v157, v211, v210, v96
	v_alignbit_b32 v158, v212, v211, v96
	v_alignbit_b32 v159, v213, v212, v96
	v_alignbit_b32 v160, v205, v204, v96
	v_alignbit_b32 v161, v206, v205, v96
	v_alignbit_b32 v162, v207, v206, v96
	v_alignbit_b32 v163, v208, v207, v96
	s_nop 0
	v_mfma_f32_32x32x16_bf16 v[4:19], v[156:159], v[230:233], v[4:19]
	v_mfma_f32_32x32x16_bf16 v[4:19], v[160:163], v[152:155], v[4:19]
	ds_read2_b32 v[204:205], v164 offset0:32 offset1:33
	ds_read2_b32 v[206:207], v164 offset0:34 offset1:35
	ds_read2_b32 v[208:209], v164 offset0:36 offset1:40
	ds_read2_b32 v[210:211], v164 offset0:41 offset1:42
	ds_read2_b32 v[212:213], v164 offset0:43 offset1:44
	ds_read_b128 v[230:233], v165 offset:5120
	ds_read_b128 v[152:155], v165 offset:5152
	s_waitcnt lgkmcnt(7)
	v_alignbit_b32 v156, v200, v199, v96
	v_alignbit_b32 v157, v201, v200, v96
	v_alignbit_b32 v158, v202, v201, v96
	v_alignbit_b32 v159, v203, v202, v96
	v_alignbit_b32 v160, v195, v194, v96
	v_alignbit_b32 v161, v196, v195, v96
	v_alignbit_b32 v162, v197, v196, v96
	v_alignbit_b32 v163, v198, v197, v96
	s_nop 0
	v_mfma_f32_32x32x16_bf16 v[4:19], v[156:159], v[222:225], v[4:19]
	v_mfma_f32_32x32x16_bf16 v[4:19], v[160:163], v[226:229], v[4:19]
	v_add_u32_e32 v164, 0x80, v164
	v_add_u32_e32 v165, 0xffffff60, v165
	s_sub_u32 s8, s8, 1
	s_cmp_lg_u32 s8, 0
	s_cbranch_scc1 .Lhy1_c
	ds_read2_b32 v[194:195], v164 offset0:16 offset1:17
	ds_read2_b32 v[196:197], v164 offset0:18 offset1:19
	ds_read2_b32 v[198:199], v164 offset0:20 offset1:24
	ds_read2_b32 v[200:201], v164 offset0:25 offset1:26
	ds_read2_b32 v[202:203], v164 offset0:27 offset1:28
	ds_read_b128 v[222:225], v165 offset:5200
	ds_read_b128 v[226:229], v165 offset:5232
	s_waitcnt lgkmcnt(7)
	v_alignbit_b32 v156, v210, v209, v96
	v_alignbit_b32 v157, v211, v210, v96
	v_alignbit_b32 v158, v212, v211, v96
	v_alignbit_b32 v159, v213, v212, v96
	v_alignbit_b32 v160, v205, v204, v96
	v_alignbit_b32 v161, v206, v205, v96
	v_alignbit_b32 v162, v207, v206, v96
	v_alignbit_b32 v163, v208, v207, v96
	s_nop 0
	v_mfma_f32_32x32x16_bf16 v[4:19], v[156:159], v[230:233], v[4:19]
	v_mfma_f32_32x32x16_bf16 v[4:19], v[160:163], v[152:155], v[4:19]
	s_waitcnt lgkmcnt(0)
	v_alignbit_b32 v156, v200, v199, v96
	v_alignbit_b32 v157, v201, v200, v96
	v_alignbit_b32 v158, v202, v201, v96
	v_alignbit_b32 v159, v203, v202, v96
	v_alignbit_b32 v160, v195, v194, v96
	v_alignbit_b32 v161, v196, v195, v96
	v_alignbit_b32 v162, v197, v196, v96
	v_alignbit_b32 v163, v198, v197, v96
	s_nop 0
	v_mfma_f32_32x32x16_bf16 v[4:19], v[156:159], v[222:225], v[4:19]
	v_mfma_f32_32x32x16_bf16 v[4:19], v[160:163], v[226:229], v[4:19]
	v_add_u32_e32 v164, 0x80, v164
	v_add_u32_e32 v165, 0xffffff60, v165
	s_waitcnt vmcnt(0) lgkmcnt(0)
	s_nop 7
	s_nop 3
	s_branch .LBB0_816
.LBB0_816:
	s_or_b64 exec, exec, s[12:13]
	v_sub_u32_e32 v0, v97, v99
	v_add_u32_e32 v44, v0, v103
	v_lshl_add_u32 v56, v75, 12, s15
	v_mad_i32_i24 v0, v44, s88, v60
	v_ashrrev_i32_e32 v57, 31, v56
	ds_read_b128 v[90:93], v0 offset:2560
	ds_read_b128 v[114:117], v0 offset:2592
	v_lshl_add_u64 v[0:1], v[56:57], 1, s[36:37]
	s_mov_b64 s[8:9], 0x880000
	v_and_b32_e32 v89, 0x5f, v70
	v_lshl_add_u64 v[84:85], v[0:1], 0, s[8:9]
	v_lshlrev_b32_e32 v2, 6, v89
	v_lshl_add_u64 v[0:1], v[84:85], 0, v[2:3]
	v_mov_b32_e32 v75, v3
	v_lshl_add_u64 v[86:87], v[0:1], 0, v[74:75]
	s_waitcnt lgkmcnt(0)
	s_barrier
	global_load_dwordx2 v[94:95], v[86:87], off
	global_load_dwordx2 v[122:123], v[86:87], off offset:16
	s_add_u32 s8, s10, 0x400000
	v_add_f32_e32 v1, v40, v41
	s_addc_u32 s9, s11, 0
	v_add_f32_e32 v1, v1, v42
	v_mul_i32_i24_e32 v88, 0x50, v44
	v_lshl_add_u64 v[40:41], v[62:63], 1, s[8:9]
	v_lshl_add_u64 v[44:45], v[64:65], 1, s[8:9]
	v_lshl_add_u64 v[48:49], v[66:67], 1, s[8:9]
	v_lshl_add_u64 v[52:53], v[68:69], 1, s[8:9]
	v_add_f32_e32 v1, v1, v43
	global_load_dwordx2 v[132:133], v[86:87], off offset:32
	s_nop 0
	global_load_dwordx4 v[40:43], v[40:41], off
	s_nop 0
	global_load_dwordx4 v[44:47], v[44:45], off
	s_nop 0
	global_load_dwordx4 v[48:51], v[48:49], off
	s_nop 0
	global_load_dwordx4 v[52:55], v[52:53], off
	v_xad_u32 v59, v74, 8, v113
	v_alignbit_b32 v119, v78, v77, v96
	v_alignbit_b32 v120, v79, v78, v96
	v_mov_b32_e32 v78, v31
	v_mad_u32_u24 v31, v89, s88, v59
	v_alignbit_b32 v118, v77, v76, v96
	v_mov_b32_e32 v76, v33
	v_add_u32_e32 v33, 0x800, v31
	ds_read2_b64 v[62:65], v33 offset0:64 offset1:66
	ds_read2_b64 v[66:69], v33 offset0:68 offset1:70
	global_load_dwordx2 v[86:87], v[86:87], off offset:48
	v_add_f32_e32 v1, 0x358637bd, v1
	v_div_scale_f32 v2, s[8:9], v1, v1, 1.0
	v_mov_b32_e32 v126, v27
	v_rcp_f32_e32 v27, v2
	v_mov_b32_e32 v124, v29
	v_mov_b32_e32 v128, v25
	v_div_scale_f32 v25, vcc, 1.0, v1, 1.0
	v_fma_f32 v29, -v2, v27, 1.0
	v_fmac_f32_e32 v27, v29, v27
	v_mul_f32_e32 v29, v25, v27
	v_mov_b32_e32 v0, v35
	v_fma_f32 v35, -v2, v29, v25
	v_fmac_f32_e32 v29, v35, v27
	v_fma_f32 v2, -v2, v29, v25
	v_div_fmas_f32 v2, v2, v27, v29
	v_lshlrev_b32_e32 v58, 2, v112
	v_mov_b32_e32 v112, v21
	s_waitcnt lgkmcnt(1)
; DI float bf2f(bf16_t v) { return __uint_as_float(((unsigned)v) << 16); }
; DI unsigned pack2(float lo, float hi) { unsigned r; asm("v_cvt_pk_bf16_f32 %0, %1, %2" : "=v"(r) : "v"(lo), "v"(hi)); return r; }
; DI void hyena_lat_item(const Params& p, int layer, int it, unsigned char* smem) {
;     ...
;       for (int n = 0; n < 2; ++n)
; #pragma unroll
;         for (int rg = 0; rg < 4; ++rg) {
;             const int a = 32 * (nbase + n) + li, ii = 8 * rg + 4 * lh; bf16_t* up = ub + a * 40 + 8 * rg + 4 * (1 - lh);
;             const u32x2 zz = *(const u32x2*)up; const u32x2 pp = *(const u32x2*)(P + (size_t)(256 + ch) * NT + bg * SEQ + 32 * a + ii);
;             float z[4] = { bf2f((bf16_t)(zz.y >> 16)), bf2f((bf16_t)(zz.y & 0xffff)), bf2f((bf16_t)(zz.x >> 16)), bf2f((bf16_t)(zz.x & 0xffff)) };
;             float q[4] = { bf2f((bf16_t)(pp.x & 0xffff)), bf2f((bf16_t)(pp.x >> 16)), bf2f((bf16_t)(pp.y & 0xffff)), bf2f((bf16_t)(pp.y >> 16)) };
;             float o[4];
; #pragma unroll
;             for (int e = 0; e < 4; ++e) o[e] = q[e] * (acc[n][4 * rg + e] * inv0 + z[e] * d0);
;             u32x2 w; w.x = pack2(o[3], o[2]); w.y = pack2(o[1], o[0]); *(u32x2*)up = w;
	v_and_b32_e32 v21, 0xffff0000, v63
	v_div_fixup_f32 v70, v2, v1, 1.0
	v_lshlrev_b32_e32 v113, 16, v63
	v_pk_mul_f32 v[20:21], v[70:71], v[20:21]
	v_mov_b32_e32 v130, v23
	v_and_b32_e32 v23, 0xffff0000, v62
	v_add_f32_e32 v1, v20, v21
	v_pk_mul_f32 v[20:21], v[70:71], v[112:113]
	v_lshlrev_b32_e32 v131, 16, v62
	v_or_b32_e32 v35, 32, v89
	v_lshlrev_b32_e32 v129, 16, v65
	v_lshlrev_b32_e32 v127, 16, v64
	s_waitcnt lgkmcnt(0)
	v_lshlrev_b32_e32 v125, 16, v67
	v_alignbit_b32 v121, v72, v79, v96
	v_lshlrev_b32_e32 v79, 16, v66
	v_lshlrev_b32_e32 v77, 16, v69
	v_alignbit_b32 v80, v81, v80, v96
	v_alignbit_b32 v81, v82, v81, v96
	v_alignbit_b32 v82, v83, v82, v96
	v_alignbit_b32 v83, v73, v83, v96
	v_mul_u32_u24_e32 v73, 0x50, v89
	v_lshlrev_b32_e32 v72, 5, v89
	s_nop 0
	s_mov_b64 s[10:11], 0
	s_waitcnt vmcnt(7)
	v_lshlrev_b32_e32 v2, 16, v94
	v_mul_f32_e32 v1, v1, v2
	v_add_f32_e32 v2, v20, v21
	v_pk_mul_f32 v[20:21], v[70:71], v[22:23]
	v_and_b32_e32 v25, 0xffff0000, v94
	v_lshlrev_b32_e32 v27, 16, v95
	v_add_f32_e32 v20, v20, v21
	v_mul_f32_e32 v2, v2, v25
	v_mul_f32_e32 v22, v20, v27
	v_pk_mul_f32 v[20:21], v[70:71], v[130:131]
	v_and_b32_e32 v23, 0xffff0000, v65
	v_add_f32_e32 v20, v20, v21
	v_cvt_pk_bf16_f32 v21, v2, v1
	v_lshlrev_b32_e32 v2, 6, v35
	v_lshl_add_u64 v[62:63], v[84:85], 0, v[2:3]
	v_and_b32_e32 v25, 0xffff0000, v64
	v_lshl_add_u64 v[64:65], v[62:63], 0, v[74:75]
	v_and_b32_e32 v29, 0xffff0000, v95
	global_load_dwordx2 v[74:75], v[64:65], off
	v_mul_f32_e32 v20, v20, v29
	v_cvt_pk_bf16_f32 v20, v20, v22
	v_mov_b32_e32 v22, v24
	v_pk_mul_f32 v[22:23], v[70:71], v[22:23]
	s_waitcnt vmcnt(7)
	v_lshlrev_b32_e32 v1, 16, v122
	v_add_f32_e32 v22, v22, v23
	v_mul_f32_e32 v1, v22, v1
	v_pk_mul_f32 v[22:23], v[70:71], v[128:129]
	v_and_b32_e32 v2, 0xffff0000, v122
	v_add_f32_e32 v22, v22, v23
	v_mov_b32_e32 v24, v26
	v_mul_f32_e32 v2, v22, v2
	v_pk_mul_f32 v[22:23], v[70:71], v[24:25]
	v_lshlrev_b32_e32 v27, 16, v123
	v_add_f32_e32 v22, v22, v23
	v_mul_f32_e32 v24, v22, v27
	v_pk_mul_f32 v[22:23], v[70:71], v[126:127]
	v_and_b32_e32 v29, 0xffff0000, v123
	v_add_f32_e32 v22, v22, v23
	v_mul_f32_e32 v22, v22, v29
	v_cvt_pk_bf16_f32 v22, v22, v24
	global_load_dwordx2 v[24:25], v[64:65], off offset:16
	v_cvt_pk_bf16_f32 v23, v2, v1
	ds_write2_b64 v33, v[20:21], v[22:23] offset0:64 offset1:66
	v_and_b32_e32 v21, 0xffff0000, v67
	v_mov_b32_e32 v20, v28
	v_pk_mul_f32 v[20:21], v[70:71], v[20:21]
	s_waitcnt vmcnt(7)
	v_lshlrev_b32_e32 v1, 16, v132
	v_add_f32_e32 v20, v20, v21
	v_mul_f32_e32 v1, v20, v1
	v_pk_mul_f32 v[20:21], v[70:71], v[124:125]
	v_and_b32_e32 v23, 0xffff0000, v66
	v_and_b32_e32 v2, 0xffff0000, v132
	v_add_f32_e32 v20, v20, v21
	v_mov_b32_e32 v22, v30
	v_mul_f32_e32 v2, v20, v2
	v_pk_mul_f32 v[20:21], v[70:71], v[22:23]
	v_lshlrev_b32_e32 v26, 16, v133
	v_add_f32_e32 v20, v20, v21
	global_load_dwordx2 v[28:29], v[64:65], off offset:32
	v_mul_f32_e32 v22, v20, v26
	v_pk_mul_f32 v[20:21], v[70:71], v[78:79]
	v_and_b32_e32 v27, 0xffff0000, v133
	v_add_f32_e32 v20, v20, v21
	v_mul_f32_e32 v20, v20, v27
	v_cvt_pk_bf16_f32 v26, v20, v22
	v_and_b32_e32 v21, 0xffff0000, v69
	v_mov_b32_e32 v20, v32
	v_pk_mul_f32 v[20:21], v[70:71], v[20:21]
	v_cvt_pk_bf16_f32 v27, v2, v1
	s_waitcnt vmcnt(3)
	v_lshlrev_b32_e32 v2, 16, v86
	v_add_f32_e32 v20, v20, v21
	v_mul_f32_e32 v2, v20, v2
	v_pk_mul_f32 v[20:21], v[70:71], v[76:77]
	v_lshlrev_b32_e32 v1, 16, v68
	v_and_b32_e32 v22, 0xffff0000, v86
	v_add_f32_e32 v20, v20, v21
	v_and_b32_e32 v23, 0xffff0000, v68
	v_mul_f32_e32 v32, v20, v22
	v_mov_b32_e32 v22, v34
	v_pk_mul_f32 v[0:1], v[70:71], v[0:1]
	v_and_b32_e32 v62, 0xffff0000, v87
	v_pk_mul_f32 v[20:21], v[70:71], v[22:23]
	v_add_f32_e32 v0, v0, v1
	v_lshlrev_b32_e32 v30, 16, v87
	v_add_f32_e32 v20, v20, v21
	v_mul_f32_e32 v0, v0, v62
	v_mul_f32_e32 v30, v20, v30
	v_cvt_pk_bf16_f32 v0, v0, v30
	v_cvt_pk_bf16_f32 v1, v32, v2
	ds_write2_b64 v33, v[26:27], v[0:1] offset0:68 offset1:70
	global_load_dwordx2 v[32:33], v[64:65], off offset:48
	s_nop 0
	v_add_u32_e32 v34, 0x1000, v31
	ds_read2_b64 v[20:23], v34 offset0:128 offset1:130
	v_lshlrev_b32_e32 v62, 5, v35
	s_waitcnt lgkmcnt(0)
	v_and_b32_e32 v1, 0xffff0000, v21
	v_lshlrev_b32_e32 v21, 16, v21
	s_nop 5
	v_mov_b32_e32 v0, v4
	v_pk_mul_f32 v[0:1], v[70:71], v[0:1]
	v_and_b32_e32 v27, 0xffff0000, v20
	v_lshlrev_b32_e32 v31, 16, v20
	s_waitcnt vmcnt(3)
; DI float bf2f(bf16_t v) { return __uint_as_float(((unsigned)v) << 16); }
; DI unsigned pack2(float lo, float hi) { unsigned r; asm("v_cvt_pk_bf16_f32 %0, %1, %2" : "=v"(r) : "v"(lo), "v"(hi)); return r; }
; DI f32x16 zero16() { f32x16 z; _Pragma("unroll") for (int i = 0; i < 16; ++i) z[i] = 0.f; return z; }
; DI void hy_conv(const bf16_t* ub, const bf16_t* filt, f32x16 (&acc)[2], int nbase, int li, int lh) {
;     const int klo = 32 * nbase - 127, khi = 32 * (nbase + 1) + 31;
;     const int m0 = 4096 + li - 8 * lh - 7;
;     const unsigned sh = (unsigned)(m0 & 1) * 16u;
;     const unsigned* fd0 = (const unsigned*)filt + (m0 >> 1);
;     unsigned raw[10];
;     hy_rawload(fd0 + 16 * klo, raw);
; DI void hyena_lat_item(const Params& p, int layer, int it, unsigned char* smem) {
;     ...
;       for (int n = 0; n < 2; ++n)
; #pragma unroll
;         for (int rg = 0; rg < 4; ++rg) {
;             const int a = 32 * (nbase + n) + li, ii = 8 * rg + 4 * lh; bf16_t* up = ub + a * 40 + 8 * rg + 4 * (1 - lh);
;             const u32x2 zz = *(const u32x2*)up; const u32x2 pp = *(const u32x2*)(P + (size_t)(256 + ch) * NT + bg * SEQ + 32 * a + ii);
;             float z[4] = { bf2f((bf16_t)(zz.y >> 16)), bf2f((bf16_t)(zz.y & 0xffff)), bf2f((bf16_t)(zz.x >> 16)), bf2f((bf16_t)(zz.x & 0xffff)) };
;             float q[4] = { bf2f((bf16_t)(pp.x & 0xffff)), bf2f((bf16_t)(pp.x >> 16)), bf2f((bf16_t)(pp.y & 0xffff)), bf2f((bf16_t)(pp.y >> 16)) };
;             float o[4];
; #pragma unroll
;             for (int e = 0; e < 4; ++e) o[e] = q[e] * (acc[n][4 * rg + e] * inv0 + z[e] * d0);
;             u32x2 w; w.x = pack2(o[3], o[2]); w.y = pack2(o[1], o[0]); *(u32x2*)up = w;
;         }
; #pragma unroll
;       for (int j = 0; j < 4; ++j) *(u32x4*)(Fl + (tid + 256 * j) * 8) = sf[j]; }
;     __syncthreads();
;     acc[0] = zero16(); acc[1] = zero16();
;     hy_conv(ub, Fl, acc, nbase, li, lh);
	v_lshlrev_b32_e32 v2, 16, v74
	v_add_f32_e32 v0, v0, v1
	v_mov_b32_e32 v20, v5
	v_mul_f32_e32 v2, v0, v2
	v_pk_mul_f32 v[0:1], v[70:71], v[20:21]
	v_and_b32_e32 v26, 0xffff0000, v74
	v_add_f32_e32 v0, v0, v1
	v_mul_f32_e32 v4, v0, v26
	v_mov_b32_e32 v26, v6
	v_pk_mul_f32 v[0:1], v[70:71], v[26:27]
	v_lshlrev_b32_e32 v30, 16, v75
	v_add_f32_e32 v0, v0, v1
	v_mul_f32_e32 v5, v0, v30
	v_mov_b32_e32 v30, v7
	v_pk_mul_f32 v[0:1], v[70:71], v[30:31]
	v_and_b32_e32 v35, 0xffff0000, v75
	v_add_f32_e32 v0, v0, v1
	v_mul_f32_e32 v0, v0, v35
	v_cvt_pk_bf16_f32 v0, v0, v5
	v_cvt_pk_bf16_f32 v1, v4, v2
	v_and_b32_e32 v5, 0xffff0000, v23
	v_mov_b32_e32 v4, v8
	v_pk_mul_f32 v[4:5], v[70:71], v[4:5]
	v_lshlrev_b32_e32 v7, 16, v23
	s_waitcnt vmcnt(2)
	v_lshlrev_b32_e32 v2, 16, v24
	v_add_f32_e32 v4, v4, v5
	v_mov_b32_e32 v6, v9
	v_mul_f32_e32 v2, v4, v2
	v_pk_mul_f32 v[4:5], v[70:71], v[6:7]
	v_and_b32_e32 v20, 0xffff0000, v24
	v_add_f32_e32 v4, v4, v5
	v_and_b32_e32 v21, 0xffff0000, v22
	v_mul_f32_e32 v9, v4, v20
	v_mov_b32_e32 v20, v10
	v_pk_mul_f32 v[4:5], v[70:71], v[20:21]
	v_lshlrev_b32_e32 v23, 16, v22
	v_lshlrev_b32_e32 v22, 16, v25
	v_add_f32_e32 v4, v4, v5
	v_mul_f32_e32 v8, v4, v22
	v_mov_b32_e32 v22, v11
	v_pk_mul_f32 v[4:5], v[70:71], v[22:23]
	v_and_b32_e32 v24, 0xffff0000, v25
	v_add_f32_e32 v10, v4, v5
	ds_read2_b64 v[4:7], v34 offset0:132 offset1:134
	v_mul_f32_e32 v10, v10, v24
	v_cvt_pk_bf16_f32 v8, v10, v8
	v_cvt_pk_bf16_f32 v9, v9, v2
	ds_write2_b64 v34, v[0:1], v[8:9] offset0:128 offset1:130
	s_waitcnt lgkmcnt(1)
	v_and_b32_e32 v1, 0xffff0000, v5
	v_mov_b32_e32 v0, v12
	v_pk_mul_f32 v[0:1], v[70:71], v[0:1]
	v_lshlrev_b32_e32 v5, 16, v5
	v_and_b32_e32 v9, 0xffff0000, v4
	v_lshlrev_b32_e32 v11, 16, v4
	s_waitcnt vmcnt(1)
	v_lshlrev_b32_e32 v2, 16, v28
	v_add_f32_e32 v0, v0, v1
	v_mov_b32_e32 v4, v13
	v_mul_f32_e32 v2, v0, v2
	v_pk_mul_f32 v[0:1], v[70:71], v[4:5]
	v_and_b32_e32 v8, 0xffff0000, v28
	v_add_f32_e32 v0, v0, v1
	v_mul_f32_e32 v4, v0, v8
	v_mov_b32_e32 v8, v14
	v_pk_mul_f32 v[0:1], v[70:71], v[8:9]
	v_lshlrev_b32_e32 v10, 16, v29
	v_add_f32_e32 v0, v0, v1
	v_mul_f32_e32 v5, v0, v10
	v_mov_b32_e32 v10, v15
	v_pk_mul_f32 v[0:1], v[70:71], v[10:11]
	v_and_b32_e32 v20, 0xffff0000, v29
	v_add_f32_e32 v0, v0, v1
	v_mul_f32_e32 v0, v0, v20
	v_cvt_pk_bf16_f32 v0, v0, v5
	v_cvt_pk_bf16_f32 v1, v4, v2
	v_and_b32_e32 v5, 0xffff0000, v7
	v_mov_b32_e32 v4, v16
	v_pk_mul_f32 v[4:5], v[70:71], v[4:5]
	v_lshlrev_b32_e32 v7, 16, v7
	v_and_b32_e32 v9, 0xffff0000, v6
	v_lshlrev_b32_e32 v11, 16, v6
	s_waitcnt vmcnt(0)
	v_lshlrev_b32_e32 v2, 16, v32
	v_add_f32_e32 v4, v4, v5
	v_mov_b32_e32 v6, v17
	v_mul_f32_e32 v2, v4, v2
	v_pk_mul_f32 v[4:5], v[70:71], v[6:7]
	v_and_b32_e32 v8, 0xffff0000, v32
	v_add_f32_e32 v4, v4, v5
	v_mul_f32_e32 v6, v4, v8
	v_mov_b32_e32 v8, v18
	v_pk_mul_f32 v[4:5], v[70:71], v[8:9]
	v_lshlrev_b32_e32 v10, 16, v33
	v_add_f32_e32 v4, v4, v5
	v_mul_f32_e32 v7, v4, v10
	v_mov_b32_e32 v10, v19
	v_pk_mul_f32 v[4:5], v[70:71], v[10:11]
	v_and_b32_e32 v12, 0xffff0000, v33
	v_add_f32_e32 v4, v4, v5
	v_mul_f32_e32 v4, v4, v12
	v_cvt_pk_bf16_f32 v4, v4, v7
	v_cvt_pk_bf16_f32 v5, v6, v2
	ds_write2_b64 v34, v[0:1], v[4:5] offset0:132 offset1:134
	ds_write_b128 v106, v[40:43] offset:30720
	ds_write_b128 v106, v[44:47] offset:34816
	ds_write_b128 v106, v[48:51] offset:38912
	ds_write_b128 v106, v[52:55] offset:43008
	s_waitcnt lgkmcnt(0)
	s_barrier
	ds_read2_b32 v[64:65], v111 offset0:124 offset1:132
	ds_read2_b32 v[70:71], v107 offset1:1
	ds_read2_b32 v[74:75], v108 offset1:1
	ds_read2_b32 v[66:67], v109 offset1:1
	ds_read2_b32 v[68:69], v110 offset1:1
	v_mov_b32_e32 v14, v3
	v_mov_b32_e32 v15, v3
	v_mov_b32_e32 v0, v3
	v_mov_b32_e32 v1, v3
	v_mov_b32_e32 v2, v3
	v_mov_b32_e32 v4, v3
	v_mov_b32_e32 v5, v3
	v_mov_b32_e32 v6, v3
	v_mov_b32_e32 v7, v3
	v_mov_b32_e32 v8, v3
	v_mov_b32_e32 v9, v3
	v_mov_b32_e32 v10, v3
	v_mov_b32_e32 v11, v3
	v_mov_b32_e32 v12, v3
	v_mov_b32_e32 v13, v3
	v_mov_b64_e32 v[34:35], v[14:15]
	v_mov_b64_e32 v[32:33], v[12:13]
	v_mov_b64_e32 v[30:31], v[10:11]
	v_mov_b64_e32 v[28:29], v[8:9]
	v_mov_b64_e32 v[26:27], v[6:7]
	v_mov_b64_e32 v[24:25], v[4:5]
	v_mov_b64_e32 v[22:23], v[2:3]
	v_mov_b64_e32 v[20:21], v[0:1]
	v_mov_b64_e32 v[18:19], v[14:15]
	v_mov_b64_e32 v[16:17], v[12:13]
	v_mov_b64_e32 v[14:15], v[10:11]
	v_mov_b64_e32 v[12:13], v[8:9]
	v_mov_b64_e32 v[10:11], v[6:7]
	v_mov_b64_e32 v[8:9], v[4:5]
	v_mov_b64_e32 v[6:7], v[2:3]
	v_mov_b64_e32 v[4:5], v[0:1]
	v_add_u32_e32 v164, 0xffffffe0, v107
	v_add_u32_e32 v165, v98, v97
	v_sub_u32_e32 v165, v165, v101
	v_add_u32_e32 v165, -2, v165
	v_mad_u32_u24 v165, v165, s88, v60
	ds_read2_b32 v[194:195], v164 offset0:0 offset1:1
	ds_read2_b32 v[196:197], v164 offset0:2 offset1:3
	ds_read2_b32 v[198:199], v164 offset0:4 offset1:8
	ds_read2_b32 v[200:201], v164 offset0:9 offset1:10
	ds_read2_b32 v[202:203], v164 offset0:11 offset1:12
	ds_read_b128 v[214:217], v165 offset:2720
	ds_read_b128 v[218:221], v165 offset:2752
	s_mov_b32 s8, 15
